# in-projection epilogue stage 2: the 16 partial-sum LDS reads of each 128-column half issued together up front (one wait) instead of one exposed LDS round trip per 16-row block
# baseline (speedup 1.0000x reference)
; #define LAS __attribute__((address_space(3)))
; __device__ __forceinline__ unsigned pk2(float lo, float hi) { unsigned r; asm volatile("v_cvt_pk_bf16_f32 %0, %1, %2" : "=v"(r) : "v"(lo), "v"(hi)); return r; }
;     __device__ __forceinline__ void operator()(const f32x4 (&acc)[2][2][4][2], const Unit& u, int wr, int wc, int fr, int fq) const {
;     ...
; #pragma unroll
;             for (int ai = 0; ai < 2; ++ai)
; #pragma unroll
;                 for (int m = 0; m < 4; ++m) {
;                     f32x4 v0 = acc[ai][bj][m][0], v1 = acc[ai][bj][m][1];
;                     if (gp[bj]) {
;                         const float tot = *(const LAS float*)(Pb + pown + ((ai * 4 + m) * 2 + bj) * 64) + *(const LAS float*)(Pb + ppar + ((ai * 4 + m) * 2 + bj) * 64);
;                         const float rs = rsqrtf(tot * (1.0f / 64.0f) + 1e-6f);
; #pragma unroll
;                         for (int e = 0; e < 4; ++e) { v0[e] = v0[e] * rs * g0[e]; v1[e] = v1[e] * rs * g1[e]; }
;                     }
;                     u32x4 w; w.x = pk2(v0[0], v0[1]); w.y = pk2(v0[2], v0[3]); w.z = pk2(v1[0], v1[1]); w.w = pk2(v1[2], v1[3]);
;                     *(u32x4*)(O + (size_t)(row0 + ai * HALF + m * 16) * NP1 + col0 + bj * HALF) = w;
;                     __builtin_amdgcn_sched_barrier(0);
;                 }
.LBB0_887:
	v_add_u32_e32 v152, 0x21900, v160
	v_add_u32_e32 v153, 0x21900, v159
	ds_read_b32 v184, v152
	ds_read_b32 v218, v153
	ds_read_b32 v185, v152 offset:128
	ds_read_b32 v219, v153 offset:128
	ds_read_b32 v186, v152 offset:256
	ds_read_b32 v220, v153 offset:256
	ds_read_b32 v187, v152 offset:384
	ds_read_b32 v221, v153 offset:384
	s_waitcnt lgkmcnt(6)
	ds_read_b32 v188, v152 offset:512
	ds_read_b32 v222, v153 offset:512
	ds_read_b32 v189, v152 offset:640
	ds_read_b32 v223, v153 offset:640
	ds_read_b32 v190, v152 offset:768
	ds_read_b32 v224, v153 offset:768
	ds_read_b32 v191, v152 offset:896
	ds_read_b32 v225, v153 offset:896
	s_waitcnt lgkmcnt(0)
	v_add_f32_e32 v152, v184, v218
	v_fmamk_f32 v152, v152, 0x3c800000, v193
	v_cmp_gt_f32_e32 vcc, s68, v152
	v_mul_f32_e32 v153, 0x4b800000, v152
	s_nop 0
	v_cndmask_b32_e32 v152, v152, v153, vcc
	v_rsq_f32_e32 v152, v152
	s_nop 0
	v_mul_f32_e32 v153, 0x45800000, v152
	v_cndmask_b32_e32 v152, v152, v153, vcc
	v_pk_mul_f32 v[126:127], v[126:127], v[152:153] op_sel_hi:[1,0]
	v_pk_mul_f32 v[122:123], v[122:123], v[152:153] op_sel_hi:[1,0]
	v_pk_mul_f32 v[128:129], v[128:129], v[152:153] op_sel_hi:[1,0]
	v_pk_mul_f32 v[124:125], v[124:125], v[152:153] op_sel_hi:[1,0]
	v_pk_mul_f32 v[126:127], v[148:149], v[126:127]
	v_pk_mul_f32 v[122:123], v[150:151], v[122:123]
	v_pk_mul_f32 v[128:129], v[144:145], v[128:129]
	v_pk_mul_f32 v[124:125], v[146:147], v[124:125]
.LBB0_888:
	v_lshl_add_u32 v161, s50, 8, v139
	v_or_b32_e32 v152, s20, v157
	v_cvt_pk_bf16_f32 v126, v126, v127
	v_cvt_pk_bf16_f32 v127, v128, v129
	v_cvt_pk_bf16_f32 v128, v122, v123
	v_mov_b64_e32 v[122:123], s[34:35]
	v_ashrrev_i32_e32 v153, 31, v152
	v_mad_i64_i32 v[122:123], s[20:21], v161, s4, v[122:123]
	v_lshl_add_u64 v[122:123], v[152:153], 1, v[122:123]
	v_cvt_pk_bf16_f32 v129, v124, v125
	global_store_dwordx4 v[122:123], v[126:129], off
	s_and_b64 vcc, exec, s[40:41]
	s_cbranch_vccnz .LBB0_890
	v_add_f32_e32 v124, v185, v219
	v_fmamk_f32 v124, v124, 0x3c800000, v193
	v_cmp_gt_f32_e32 vcc, s68, v124
	v_mul_f32_e32 v125, 0x4b800000, v124
	s_nop 0
	v_cndmask_b32_e32 v124, v124, v125, vcc
	v_rsq_f32_e32 v124, v124
	s_nop 0
	v_mul_f32_e32 v125, 0x45800000, v124
	v_cndmask_b32_e32 v124, v124, v125, vcc
	v_pk_mul_f32 v[118:119], v[118:119], v[124:125] op_sel_hi:[1,0]
	v_pk_mul_f32 v[114:115], v[114:115], v[124:125] op_sel_hi:[1,0]
	v_pk_mul_f32 v[120:121], v[120:121], v[124:125] op_sel_hi:[1,0]
	v_pk_mul_f32 v[116:117], v[116:117], v[124:125] op_sel_hi:[1,0]
	v_pk_mul_f32 v[118:119], v[148:149], v[118:119]
	v_pk_mul_f32 v[114:115], v[150:151], v[114:115]
	v_pk_mul_f32 v[120:121], v[144:145], v[120:121]
	v_pk_mul_f32 v[116:117], v[146:147], v[116:117]
.LBB0_890:
	v_cvt_pk_bf16_f32 v118, v118, v119
	v_cvt_pk_bf16_f32 v119, v120, v121
	v_cvt_pk_bf16_f32 v120, v114, v115
	s_nop 0
	v_cvt_pk_bf16_f32 v121, v116, v117
	v_or_b32_e32 v116, 16, v161
	v_mov_b64_e32 v[114:115], s[34:35]
	v_mad_i64_i32 v[114:115], s[20:21], v116, s4, v[114:115]
	v_lshl_add_u64 v[114:115], v[152:153], 1, v[114:115]
	global_store_dwordx4 v[114:115], v[118:121], off
	s_and_b64 vcc, exec, s[40:41]
	s_cbranch_vccnz .LBB0_892
	v_add_f32_e32 v116, v186, v220
	v_fmamk_f32 v116, v116, 0x3c800000, v193
	v_cmp_gt_f32_e32 vcc, s68, v116
	v_mul_f32_e32 v117, 0x4b800000, v116
	s_nop 0
	v_cndmask_b32_e32 v116, v116, v117, vcc
	v_rsq_f32_e32 v116, v116
	s_nop 0
	v_mul_f32_e32 v117, 0x45800000, v116
	v_cndmask_b32_e32 v116, v116, v117, vcc
	v_pk_mul_f32 v[110:111], v[110:111], v[116:117] op_sel_hi:[1,0]
	v_pk_mul_f32 v[106:107], v[106:107], v[116:117] op_sel_hi:[1,0]
	v_pk_mul_f32 v[112:113], v[112:113], v[116:117] op_sel_hi:[1,0]
	v_pk_mul_f32 v[108:109], v[108:109], v[116:117] op_sel_hi:[1,0]
	v_pk_mul_f32 v[110:111], v[148:149], v[110:111]
	v_pk_mul_f32 v[106:107], v[150:151], v[106:107]
	v_pk_mul_f32 v[112:113], v[144:145], v[112:113]
	v_pk_mul_f32 v[108:109], v[146:147], v[108:109]
.LBB0_892:
	v_cvt_pk_bf16_f32 v110, v110, v111
	v_cvt_pk_bf16_f32 v111, v112, v113
	v_cvt_pk_bf16_f32 v112, v106, v107
	s_nop 0
	v_cvt_pk_bf16_f32 v113, v108, v109
	v_or_b32_e32 v108, 32, v161
	v_mov_b64_e32 v[106:107], s[34:35]
	v_mad_i64_i32 v[106:107], s[20:21], v108, s4, v[106:107]
	v_lshl_add_u64 v[106:107], v[152:153], 1, v[106:107]
	global_store_dwordx4 v[106:107], v[110:113], off
	s_and_b64 vcc, exec, s[40:41]
	s_cbranch_vccnz .LBB0_894
	v_add_f32_e32 v108, v187, v221
	v_fmamk_f32 v108, v108, 0x3c800000, v193
	v_cmp_gt_f32_e32 vcc, s68, v108
	v_mul_f32_e32 v109, 0x4b800000, v108
	s_nop 0
	v_cndmask_b32_e32 v108, v108, v109, vcc
	v_rsq_f32_e32 v108, v108
	s_nop 0
	v_mul_f32_e32 v109, 0x45800000, v108
	v_cndmask_b32_e32 v108, v108, v109, vcc
	v_pk_mul_f32 v[102:103], v[102:103], v[108:109] op_sel_hi:[1,0]
	v_pk_mul_f32 v[98:99], v[98:99], v[108:109] op_sel_hi:[1,0]
	v_pk_mul_f32 v[104:105], v[104:105], v[108:109] op_sel_hi:[1,0]
	v_pk_mul_f32 v[100:101], v[100:101], v[108:109] op_sel_hi:[1,0]
	v_pk_mul_f32 v[102:103], v[148:149], v[102:103]
	v_pk_mul_f32 v[98:99], v[150:151], v[98:99]
	v_pk_mul_f32 v[104:105], v[144:145], v[104:105]
	v_pk_mul_f32 v[100:101], v[146:147], v[100:101]
; #define LAS __attribute__((address_space(3)))
; __device__ __forceinline__ unsigned pk2(float lo, float hi) { unsigned r; asm volatile("v_cvt_pk_bf16_f32 %0, %1, %2" : "=v"(r) : "v"(lo), "v"(hi)); return r; }
;     __device__ __forceinline__ void operator()(const f32x4 (&acc)[2][2][4][2], const Unit& u, int wr, int wc, int fr, int fq) const {
;     ...
; #pragma unroll
;             for (int ai = 0; ai < 2; ++ai)
; #pragma unroll
;                 for (int m = 0; m < 4; ++m) {
;                     f32x4 v0 = acc[ai][bj][m][0], v1 = acc[ai][bj][m][1];
;                     if (gp[bj]) {
;                         const float tot = *(const LAS float*)(Pb + pown + ((ai * 4 + m) * 2 + bj) * 64) + *(const LAS float*)(Pb + ppar + ((ai * 4 + m) * 2 + bj) * 64);
;                         const float rs = rsqrtf(tot * (1.0f / 64.0f) + 1e-6f);
; #pragma unroll
;                         for (int e = 0; e < 4; ++e) { v0[e] = v0[e] * rs * g0[e]; v1[e] = v1[e] * rs * g1[e]; }
;                     }
;                     u32x4 w; w.x = pk2(v0[0], v0[1]); w.y = pk2(v0[2], v0[3]); w.z = pk2(v1[0], v1[1]); w.w = pk2(v1[2], v1[3]);
;                     *(u32x4*)(O + (size_t)(row0 + ai * HALF + m * 16) * NP1 + col0 + bj * HALF) = w;
;                     __builtin_amdgcn_sched_barrier(0);
;                 }
.LBB0_894:
	v_cvt_pk_bf16_f32 v102, v102, v103
	v_cvt_pk_bf16_f32 v103, v104, v105
	v_cvt_pk_bf16_f32 v104, v98, v99
	s_nop 0
	v_cvt_pk_bf16_f32 v105, v100, v101
	v_or_b32_e32 v100, 48, v161
	v_mov_b64_e32 v[98:99], s[34:35]
	v_mad_i64_i32 v[98:99], s[20:21], v100, s4, v[98:99]
	v_lshl_add_u64 v[98:99], v[152:153], 1, v[98:99]
	global_store_dwordx4 v[98:99], v[102:105], off
	s_and_b64 vcc, exec, s[40:41]
	s_cbranch_vccnz .LBB0_896
	v_add_f32_e32 v100, v188, v222
	v_fmamk_f32 v100, v100, 0x3c800000, v193
	v_cmp_gt_f32_e32 vcc, s68, v100
	v_mul_f32_e32 v101, 0x4b800000, v100
	s_nop 0
	v_cndmask_b32_e32 v100, v100, v101, vcc
	v_rsq_f32_e32 v100, v100
	s_nop 0
	v_mul_f32_e32 v101, 0x45800000, v100
	v_cndmask_b32_e32 v100, v100, v101, vcc
	v_pk_mul_f32 v[94:95], v[94:95], v[100:101] op_sel_hi:[1,0]
	v_pk_mul_f32 v[90:91], v[90:91], v[100:101] op_sel_hi:[1,0]
	v_pk_mul_f32 v[96:97], v[96:97], v[100:101] op_sel_hi:[1,0]
	v_pk_mul_f32 v[92:93], v[92:93], v[100:101] op_sel_hi:[1,0]
	v_pk_mul_f32 v[94:95], v[148:149], v[94:95]
	v_pk_mul_f32 v[90:91], v[150:151], v[90:91]
	v_pk_mul_f32 v[96:97], v[144:145], v[96:97]
	v_pk_mul_f32 v[92:93], v[146:147], v[92:93]
.LBB0_896:
	v_add_u32_e32 v100, 0x80, v161
	v_cvt_pk_bf16_f32 v94, v94, v95
	v_cvt_pk_bf16_f32 v95, v96, v97
	v_cvt_pk_bf16_f32 v96, v90, v91
	v_mov_b64_e32 v[90:91], s[34:35]
	v_mad_i64_i32 v[90:91], s[20:21], v100, s4, v[90:91]
	v_lshl_add_u64 v[90:91], v[152:153], 1, v[90:91]
	v_cvt_pk_bf16_f32 v97, v92, v93
	global_store_dwordx4 v[90:91], v[94:97], off
	s_and_b64 vcc, exec, s[40:41]
	s_cbranch_vccnz .LBB0_898
	v_add_f32_e32 v92, v189, v223
	v_fmamk_f32 v92, v92, 0x3c800000, v193
	v_cmp_gt_f32_e32 vcc, s68, v92
	v_mul_f32_e32 v93, 0x4b800000, v92
	s_nop 0
	v_cndmask_b32_e32 v92, v92, v93, vcc
	v_rsq_f32_e32 v92, v92
	s_nop 0
	v_mul_f32_e32 v93, 0x45800000, v92
	v_cndmask_b32_e32 v92, v92, v93, vcc
	v_pk_mul_f32 v[86:87], v[86:87], v[92:93] op_sel_hi:[1,0]
	v_pk_mul_f32 v[82:83], v[82:83], v[92:93] op_sel_hi:[1,0]
	v_pk_mul_f32 v[88:89], v[88:89], v[92:93] op_sel_hi:[1,0]
	v_pk_mul_f32 v[84:85], v[84:85], v[92:93] op_sel_hi:[1,0]
	v_pk_mul_f32 v[86:87], v[148:149], v[86:87]
	v_pk_mul_f32 v[82:83], v[150:151], v[82:83]
	v_pk_mul_f32 v[88:89], v[144:145], v[88:89]
	v_pk_mul_f32 v[84:85], v[146:147], v[84:85]
.LBB0_898:
	v_cvt_pk_bf16_f32 v86, v86, v87
	v_cvt_pk_bf16_f32 v87, v88, v89
	v_cvt_pk_bf16_f32 v88, v82, v83
	s_nop 0
	v_cvt_pk_bf16_f32 v89, v84, v85
	v_add_u32_e32 v84, 0x90, v161
	v_mov_b64_e32 v[82:83], s[34:35]
	v_mad_i64_i32 v[82:83], s[20:21], v84, s4, v[82:83]
	v_lshl_add_u64 v[82:83], v[152:153], 1, v[82:83]
	global_store_dwordx4 v[82:83], v[86:89], off
	s_and_b64 vcc, exec, s[40:41]
	s_cbranch_vccnz .LBB0_900
	v_add_f32_e32 v84, v190, v224
	v_fmamk_f32 v84, v84, 0x3c800000, v193
	v_cmp_gt_f32_e32 vcc, s68, v84
	v_mul_f32_e32 v85, 0x4b800000, v84
	s_nop 0
	v_cndmask_b32_e32 v84, v84, v85, vcc
	v_rsq_f32_e32 v84, v84
	s_nop 0
	v_mul_f32_e32 v85, 0x45800000, v84
	v_cndmask_b32_e32 v84, v84, v85, vcc
	v_pk_mul_f32 v[78:79], v[78:79], v[84:85] op_sel_hi:[1,0]
	v_pk_mul_f32 v[74:75], v[74:75], v[84:85] op_sel_hi:[1,0]
	v_pk_mul_f32 v[80:81], v[80:81], v[84:85] op_sel_hi:[1,0]
	v_pk_mul_f32 v[76:77], v[76:77], v[84:85] op_sel_hi:[1,0]
	v_pk_mul_f32 v[78:79], v[148:149], v[78:79]
	v_pk_mul_f32 v[74:75], v[150:151], v[74:75]
	v_pk_mul_f32 v[80:81], v[144:145], v[80:81]
	v_pk_mul_f32 v[76:77], v[146:147], v[76:77]
.LBB0_900:
	v_cvt_pk_bf16_f32 v78, v78, v79
	v_cvt_pk_bf16_f32 v79, v80, v81
	v_cvt_pk_bf16_f32 v80, v74, v75
	s_nop 0
	v_cvt_pk_bf16_f32 v81, v76, v77
	v_add_u32_e32 v76, 0xa0, v161
	v_mov_b64_e32 v[74:75], s[34:35]
	v_mad_i64_i32 v[74:75], s[20:21], v76, s4, v[74:75]
	v_lshl_add_u64 v[74:75], v[152:153], 1, v[74:75]
	global_store_dwordx4 v[74:75], v[78:81], off
	s_and_b64 vcc, exec, s[40:41]
	s_cbranch_vccnz .LBB0_902
	v_add_f32_e32 v76, v191, v225
	v_fmamk_f32 v76, v76, 0x3c800000, v193
	v_cmp_gt_f32_e32 vcc, s68, v76
	v_mul_f32_e32 v77, 0x4b800000, v76
	s_nop 0
	v_cndmask_b32_e32 v76, v76, v77, vcc
	v_rsq_f32_e32 v76, v76
	s_nop 0
	v_mul_f32_e32 v77, 0x45800000, v76
	v_cndmask_b32_e32 v76, v76, v77, vcc
	v_pk_mul_f32 v[70:71], v[70:71], v[76:77] op_sel_hi:[1,0]
	v_pk_mul_f32 v[66:67], v[66:67], v[76:77] op_sel_hi:[1,0]
	v_pk_mul_f32 v[72:73], v[72:73], v[76:77] op_sel_hi:[1,0]
	v_pk_mul_f32 v[68:69], v[68:69], v[76:77] op_sel_hi:[1,0]
	v_pk_mul_f32 v[70:71], v[148:149], v[70:71]
	v_pk_mul_f32 v[66:67], v[150:151], v[66:67]
	v_pk_mul_f32 v[72:73], v[144:145], v[72:73]
	v_pk_mul_f32 v[68:69], v[146:147], v[68:69]

; #define LAS __attribute__((address_space(3)))
; __device__ __forceinline__ unsigned pk2(float lo, float hi) { unsigned r; asm volatile("v_cvt_pk_bf16_f32 %0, %1, %2" : "=v"(r) : "v"(lo), "v"(hi)); return r; }
;     __device__ __forceinline__ void operator()(const f32x4 (&acc)[2][2][4][2], const Unit& u, int wr, int wc, int fr, int fq) const {
;     ...
;         for (int bj = 0; bj < 2; ++bj) {
;             f32x4 g0 = (f32x4){1.f, 1.f, 1.f, 1.f}, g1 = g0;
;             if (gp[bj]) { const float* g = gp[bj] + (wc & 1) * 32 + fq * 8; g0 = *(const f32x4*)g * sc[bj]; g1 = *(const f32x4*)(g + 4) * sc[bj]; }
; #pragma unroll
;             for (int ai = 0; ai < 2; ++ai)
; #pragma unroll
;                 for (int m = 0; m < 4; ++m) {
;                     f32x4 v0 = acc[ai][bj][m][0], v1 = acc[ai][bj][m][1];
;                     if (gp[bj]) {
;                         const float tot = *(const LAS float*)(Pb + pown + ((ai * 4 + m) * 2 + bj) * 64) + *(const LAS float*)(Pb + ppar + ((ai * 4 + m) * 2 + bj) * 64);
;                         const float rs = rsqrtf(tot * (1.0f / 64.0f) + 1e-6f);
; #pragma unroll
;                         for (int e = 0; e < 4; ++e) { v0[e] = v0[e] * rs * g0[e]; v1[e] = v1[e] * rs * g1[e]; }
;                     }
;                     u32x4 w; w.x = pk2(v0[0], v0[1]); w.y = pk2(v0[2], v0[3]); w.z = pk2(v1[0], v1[1]); w.w = pk2(v1[2], v1[3]);
;                     *(u32x4*)(O + (size_t)(row0 + ai * HALF + m * 16) * NP1 + col0 + bj * HALF) = w;
;                     __builtin_amdgcn_sched_barrier(0);
;                 }
.LBB0_904:
	v_add_u32_e32 v0, 0x21900, v160
	v_add_u32_e32 v78, 0x21900, v159
	ds_read_b32 v184, v0 offset:64
	ds_read_b32 v218, v78 offset:64
	ds_read_b32 v185, v0 offset:192
	ds_read_b32 v219, v78 offset:192
	ds_read_b32 v186, v0 offset:320
	ds_read_b32 v220, v78 offset:320
	ds_read_b32 v187, v0 offset:448
	ds_read_b32 v221, v78 offset:448
	s_waitcnt lgkmcnt(6)
	ds_read_b32 v188, v0 offset:576
	ds_read_b32 v222, v78 offset:576
	ds_read_b32 v189, v0 offset:704
	ds_read_b32 v223, v78 offset:704
	ds_read_b32 v190, v0 offset:832
	ds_read_b32 v224, v78 offset:832
	ds_read_b32 v191, v0 offset:960
	ds_read_b32 v225, v78 offset:960
	s_waitcnt lgkmcnt(0)
	v_add_f32_e32 v0, v184, v218
	v_fmamk_f32 v0, v0, 0x3c800000, v193
	v_cmp_gt_f32_e32 vcc, s68, v0
	v_mul_f32_e32 v78, 0x4b800000, v0
	s_nop 0
	v_cndmask_b32_e32 v0, v0, v78, vcc
	v_rsq_f32_e32 v0, v0
	s_nop 0
	v_mul_f32_e32 v78, 0x45800000, v0
	v_cndmask_b32_e32 v0, v0, v78, vcc
	v_pk_mul_f32 v[62:63], v[62:63], v[0:1] op_sel_hi:[1,0]
	v_pk_mul_f32 v[58:59], v[58:59], v[0:1] op_sel_hi:[1,0]
	v_pk_mul_f32 v[64:65], v[64:65], v[0:1] op_sel_hi:[1,0]
	v_pk_mul_f32 v[60:61], v[60:61], v[0:1] op_sel_hi:[1,0]
	v_pk_mul_f32 v[62:63], v[72:73], v[62:63]
	v_pk_mul_f32 v[58:59], v[76:77], v[58:59]
	v_pk_mul_f32 v[64:65], v[68:69], v[64:65]
	v_pk_mul_f32 v[60:61], v[70:71], v[60:61]
.LBB0_905:
	v_cvt_pk_bf16_f32 v62, v62, v63
	v_cvt_pk_bf16_f32 v63, v64, v65
	v_cvt_pk_bf16_f32 v64, v58, v59
	s_nop 0
	v_cvt_pk_bf16_f32 v65, v60, v61
	global_store_dwordx4 v[122:123], v[62:65], off offset:256
	s_and_b64 vcc, exec, s[40:41]
	s_cbranch_vccnz .LBB0_907
	v_add_f32_e32 v0, v185, v219
	v_fmamk_f32 v0, v0, 0x3c800000, v193
	v_cmp_gt_f32_e32 vcc, s68, v0
	v_mul_f32_e32 v58, 0x4b800000, v0
	s_nop 0
	v_cndmask_b32_e32 v0, v0, v58, vcc
	v_rsq_f32_e32 v0, v0
	s_nop 0
	v_mul_f32_e32 v58, 0x45800000, v0
	v_cndmask_b32_e32 v0, v0, v58, vcc
	v_pk_mul_f32 v[54:55], v[54:55], v[0:1] op_sel_hi:[1,0]
	v_pk_mul_f32 v[50:51], v[50:51], v[0:1] op_sel_hi:[1,0]
	v_pk_mul_f32 v[56:57], v[56:57], v[0:1] op_sel_hi:[1,0]
	v_pk_mul_f32 v[52:53], v[52:53], v[0:1] op_sel_hi:[1,0]
	v_pk_mul_f32 v[54:55], v[72:73], v[54:55]
	v_pk_mul_f32 v[50:51], v[76:77], v[50:51]
	v_pk_mul_f32 v[56:57], v[68:69], v[56:57]
	v_pk_mul_f32 v[52:53], v[70:71], v[52:53]
.LBB0_907:
	v_cvt_pk_bf16_f32 v54, v54, v55
	v_cvt_pk_bf16_f32 v55, v56, v57
	v_cvt_pk_bf16_f32 v56, v50, v51
	s_nop 0
	v_cvt_pk_bf16_f32 v57, v52, v53
	global_store_dwordx4 v[114:115], v[54:57], off offset:256
	s_and_b64 vcc, exec, s[40:41]
	s_cbranch_vccnz .LBB0_909
	v_add_f32_e32 v0, v186, v220
	v_fmamk_f32 v0, v0, 0x3c800000, v193
	v_cmp_gt_f32_e32 vcc, s68, v0
	v_mul_f32_e32 v50, 0x4b800000, v0
	s_nop 0
	v_cndmask_b32_e32 v0, v0, v50, vcc
	v_rsq_f32_e32 v0, v0
	s_nop 0
	v_mul_f32_e32 v50, 0x45800000, v0
	v_cndmask_b32_e32 v0, v0, v50, vcc
	v_pk_mul_f32 v[46:47], v[46:47], v[0:1] op_sel_hi:[1,0]
	v_pk_mul_f32 v[42:43], v[42:43], v[0:1] op_sel_hi:[1,0]
	v_pk_mul_f32 v[48:49], v[48:49], v[0:1] op_sel_hi:[1,0]
	v_pk_mul_f32 v[44:45], v[44:45], v[0:1] op_sel_hi:[1,0]
	v_pk_mul_f32 v[46:47], v[72:73], v[46:47]
	v_pk_mul_f32 v[42:43], v[76:77], v[42:43]
	v_pk_mul_f32 v[48:49], v[68:69], v[48:49]
	v_pk_mul_f32 v[44:45], v[70:71], v[44:45]
.LBB0_909:
	v_cvt_pk_bf16_f32 v46, v46, v47
	v_cvt_pk_bf16_f32 v47, v48, v49
	v_cvt_pk_bf16_f32 v48, v42, v43
	s_nop 0
	v_cvt_pk_bf16_f32 v49, v44, v45
	global_store_dwordx4 v[106:107], v[46:49], off offset:256
	s_and_b64 vcc, exec, s[40:41]
	s_cbranch_vccnz .LBB0_911
	v_add_f32_e32 v0, v187, v221
	v_fmamk_f32 v0, v0, 0x3c800000, v193
	v_cmp_gt_f32_e32 vcc, s68, v0
	v_mul_f32_e32 v42, 0x4b800000, v0
	s_nop 0
	v_cndmask_b32_e32 v0, v0, v42, vcc
	v_rsq_f32_e32 v0, v0
	s_nop 0
	v_mul_f32_e32 v42, 0x45800000, v0
	v_cndmask_b32_e32 v0, v0, v42, vcc
	v_pk_mul_f32 v[38:39], v[38:39], v[0:1] op_sel_hi:[1,0]
	v_pk_mul_f32 v[34:35], v[34:35], v[0:1] op_sel_hi:[1,0]
	v_pk_mul_f32 v[40:41], v[40:41], v[0:1] op_sel_hi:[1,0]
	v_pk_mul_f32 v[36:37], v[36:37], v[0:1] op_sel_hi:[1,0]
	v_pk_mul_f32 v[38:39], v[72:73], v[38:39]
	v_pk_mul_f32 v[34:35], v[76:77], v[34:35]
	v_pk_mul_f32 v[40:41], v[68:69], v[40:41]
	v_pk_mul_f32 v[36:37], v[70:71], v[36:37]
; #define LAS __attribute__((address_space(3)))
; __device__ __forceinline__ unsigned pk2(float lo, float hi) { unsigned r; asm volatile("v_cvt_pk_bf16_f32 %0, %1, %2" : "=v"(r) : "v"(lo), "v"(hi)); return r; }
;     __device__ __forceinline__ void operator()(const f32x4 (&acc)[2][2][4][2], const Unit& u, int wr, int wc, int fr, int fq) const {
;     ...
;         for (int bj = 0; bj < 2; ++bj) {
;             f32x4 g0 = (f32x4){1.f, 1.f, 1.f, 1.f}, g1 = g0;
;             if (gp[bj]) { const float* g = gp[bj] + (wc & 1) * 32 + fq * 8; g0 = *(const f32x4*)g * sc[bj]; g1 = *(const f32x4*)(g + 4) * sc[bj]; }
; #pragma unroll
;             for (int ai = 0; ai < 2; ++ai)
; #pragma unroll
;                 for (int m = 0; m < 4; ++m) {
;                     f32x4 v0 = acc[ai][bj][m][0], v1 = acc[ai][bj][m][1];
;                     if (gp[bj]) {
;                         const float tot = *(const LAS float*)(Pb + pown + ((ai * 4 + m) * 2 + bj) * 64) + *(const LAS float*)(Pb + ppar + ((ai * 4 + m) * 2 + bj) * 64);
;                         const float rs = rsqrtf(tot * (1.0f / 64.0f) + 1e-6f);
; #pragma unroll
;                         for (int e = 0; e < 4; ++e) { v0[e] = v0[e] * rs * g0[e]; v1[e] = v1[e] * rs * g1[e]; }
;                     }
;                     u32x4 w; w.x = pk2(v0[0], v0[1]); w.y = pk2(v0[2], v0[3]); w.z = pk2(v1[0], v1[1]); w.w = pk2(v1[2], v1[3]);
;                     *(u32x4*)(O + (size_t)(row0 + ai * HALF + m * 16) * NP1 + col0 + bj * HALF) = w;
;                     __builtin_amdgcn_sched_barrier(0);
;                 }
.LBB0_911:
	v_cvt_pk_bf16_f32 v38, v38, v39
	v_cvt_pk_bf16_f32 v39, v40, v41
	v_cvt_pk_bf16_f32 v40, v34, v35
	s_nop 0
	v_cvt_pk_bf16_f32 v41, v36, v37
	global_store_dwordx4 v[98:99], v[38:41], off offset:256
	s_and_b64 vcc, exec, s[40:41]
	s_cbranch_vccnz .LBB0_913
	v_add_f32_e32 v0, v188, v222
	v_fmamk_f32 v0, v0, 0x3c800000, v193
	v_cmp_gt_f32_e32 vcc, s68, v0
	v_mul_f32_e32 v34, 0x4b800000, v0
	s_nop 0
	v_cndmask_b32_e32 v0, v0, v34, vcc
	v_rsq_f32_e32 v0, v0
	s_nop 0
	v_mul_f32_e32 v34, 0x45800000, v0
	v_cndmask_b32_e32 v0, v0, v34, vcc
	v_pk_mul_f32 v[30:31], v[30:31], v[0:1] op_sel_hi:[1,0]
	v_pk_mul_f32 v[26:27], v[26:27], v[0:1] op_sel_hi:[1,0]
	v_pk_mul_f32 v[32:33], v[32:33], v[0:1] op_sel_hi:[1,0]
	v_pk_mul_f32 v[28:29], v[28:29], v[0:1] op_sel_hi:[1,0]
	v_pk_mul_f32 v[30:31], v[72:73], v[30:31]
	v_pk_mul_f32 v[26:27], v[76:77], v[26:27]
	v_pk_mul_f32 v[32:33], v[68:69], v[32:33]
	v_pk_mul_f32 v[28:29], v[70:71], v[28:29]
.LBB0_913:
	v_cvt_pk_bf16_f32 v30, v30, v31
	v_cvt_pk_bf16_f32 v31, v32, v33
	v_cvt_pk_bf16_f32 v32, v26, v27
	s_nop 0
	v_cvt_pk_bf16_f32 v33, v28, v29
	global_store_dwordx4 v[90:91], v[30:33], off offset:256
	s_and_b64 vcc, exec, s[40:41]
	s_cbranch_vccnz .LBB0_915
	v_add_f32_e32 v0, v189, v223
	v_fmamk_f32 v0, v0, 0x3c800000, v193
	v_cmp_gt_f32_e32 vcc, s68, v0
	v_mul_f32_e32 v26, 0x4b800000, v0
	s_nop 0
	v_cndmask_b32_e32 v0, v0, v26, vcc
	v_rsq_f32_e32 v0, v0
	s_nop 0
	v_mul_f32_e32 v26, 0x45800000, v0
	v_cndmask_b32_e32 v0, v0, v26, vcc
	v_pk_mul_f32 v[22:23], v[22:23], v[0:1] op_sel_hi:[1,0]
	v_pk_mul_f32 v[18:19], v[18:19], v[0:1] op_sel_hi:[1,0]
	v_pk_mul_f32 v[24:25], v[24:25], v[0:1] op_sel_hi:[1,0]
	v_pk_mul_f32 v[20:21], v[20:21], v[0:1] op_sel_hi:[1,0]
	v_pk_mul_f32 v[22:23], v[72:73], v[22:23]
	v_pk_mul_f32 v[18:19], v[76:77], v[18:19]
	v_pk_mul_f32 v[24:25], v[68:69], v[24:25]
	v_pk_mul_f32 v[20:21], v[70:71], v[20:21]
.LBB0_915:
	v_cvt_pk_bf16_f32 v22, v22, v23
	v_cvt_pk_bf16_f32 v23, v24, v25
	v_cvt_pk_bf16_f32 v24, v18, v19
	s_nop 0
	v_cvt_pk_bf16_f32 v25, v20, v21
	global_store_dwordx4 v[82:83], v[22:25], off offset:256
	s_and_b64 vcc, exec, s[40:41]
	s_cbranch_vccnz .LBB0_917
	v_add_f32_e32 v0, v190, v224
	v_fmamk_f32 v0, v0, 0x3c800000, v193
	v_cmp_gt_f32_e32 vcc, s68, v0
	v_mul_f32_e32 v18, 0x4b800000, v0
	s_nop 0
	v_cndmask_b32_e32 v0, v0, v18, vcc
	v_rsq_f32_e32 v0, v0
	s_nop 0
	v_mul_f32_e32 v18, 0x45800000, v0
	v_cndmask_b32_e32 v0, v0, v18, vcc
	v_pk_mul_f32 v[14:15], v[14:15], v[0:1] op_sel_hi:[1,0]
	v_pk_mul_f32 v[10:11], v[10:11], v[0:1] op_sel_hi:[1,0]
	v_pk_mul_f32 v[16:17], v[16:17], v[0:1] op_sel_hi:[1,0]
	v_pk_mul_f32 v[12:13], v[12:13], v[0:1] op_sel_hi:[1,0]
	v_pk_mul_f32 v[14:15], v[72:73], v[14:15]
	v_pk_mul_f32 v[10:11], v[76:77], v[10:11]
	v_pk_mul_f32 v[16:17], v[68:69], v[16:17]
	v_pk_mul_f32 v[12:13], v[70:71], v[12:13]
.LBB0_917:
	v_cvt_pk_bf16_f32 v14, v14, v15
	v_cvt_pk_bf16_f32 v15, v16, v17
	v_cvt_pk_bf16_f32 v16, v10, v11
	s_nop 0
	v_cvt_pk_bf16_f32 v17, v12, v13
	global_store_dwordx4 v[74:75], v[14:17], off offset:256
	s_and_b64 vcc, exec, s[40:41]
	s_cbranch_vccnz .LBB0_919
	v_add_f32_e32 v0, v191, v225
	v_fmamk_f32 v0, v0, 0x3c800000, v193
	v_cmp_gt_f32_e32 vcc, s68, v0
	v_mul_f32_e32 v10, 0x4b800000, v0
	s_nop 0
	v_cndmask_b32_e32 v0, v0, v10, vcc
	v_rsq_f32_e32 v0, v0
	s_nop 0
	v_mul_f32_e32 v10, 0x45800000, v0
	v_cndmask_b32_e32 v0, v0, v10, vcc
	v_pk_mul_f32 v[6:7], v[6:7], v[0:1] op_sel_hi:[1,0]
	v_pk_mul_f32 v[2:3], v[2:3], v[0:1] op_sel_hi:[1,0]
	v_pk_mul_f32 v[8:9], v[8:9], v[0:1] op_sel_hi:[1,0]
	v_pk_mul_f32 v[4:5], v[4:5], v[0:1] op_sel_hi:[1,0]
	v_pk_mul_f32 v[6:7], v[72:73], v[6:7]
	v_pk_mul_f32 v[2:3], v[76:77], v[2:3]
	v_pk_mul_f32 v[8:9], v[68:69], v[8:9]
	v_pk_mul_f32 v[4:5], v[70:71], v[4:5]
